# select: exact-case fast path writes the key bitmask rows directly (ballot + writelane gather + 2-3 coalesced stores), skipping the generic gt/eq/tie/store sequence
# speedup vs baseline: 1.0185x; 1.0185x over previous
; DI void select_item(const Params& p, int isP, int sq, int c, int sub, char*) {
;     ...
;     if (exact) {
;       unsigned mn = 0xFFFFFFFFu;
; #pragma unroll
;       for (int r = 0; r < 65; ++r) mn = min(mn, v[r] >= thr ? v[r] : 0xFFFFFFFFu);
; #pragma unroll
;       for (int o = 32; o >= 1; o >>= 1) mn = min(mn, (unsigned)__shfl_xor((int)mn, o));
;       thr = __builtin_amdgcn_readfirstlane(mn);
;     }
;     int gt = 0, eq = 0;
; #pragma unroll
;     for (int r = 0; r < 65; ++r) {
;       gt += __popcll(__ballot(v[r] > thr));
;       eq += __popcll(__ballot(v[r] == thr));
;     }
;     const int need = 256 - gt;
;     int idxcut = 0x7fffffff;
;     if (eq != need) {
;       int run = 0;
;       bool done = false;
; #pragma unroll
;       for (int r = 0; r < 65; ++r) {
;         if (!done) {
;           unsigned long long m = __ballot(v[r] == thr);
;           int pc = __popcll(m);
;           if (run + pc >= need) {
;             const int k = need - run;
;             for (int t = 1; t < k; ++t) m &= m - 1ull;
;             idxcut = r * 64 + (__ffsll((long long)m) - 1);
;             done = true;
;           } else run += pc;
;         }
;       }
;     }
;     unsigned* mrowp = maskg + (long)(qrow + wid) * MW;
; #pragma unroll
;     for (int r = 0; r < 65; ++r) {
;       if (r < nr) {
;         const bool sel = (v[r] > thr) || (v[r] == thr && (r * 64 + lane) <= idxcut);
;         const unsigned long long bal = __ballot(sel);
;         if (lane == 0) *(uint2*)(mrowp + r * 2) = make_uint2((unsigned)bal, (unsigned)(bal >> 32));
;       }
;     }
.Lrx1_next:
	s_add_i32 s7, s7, -1
	s_cmp_ge_i32 s7, 0
	s_cbranch_scc1 .Lrx1_top
	s_branch .LBB0_2808
.Lrx1_fast:
	s_add_i32 s0, s29, s81
	s_mul_hi_i32 s1, s0, 0x210
	s_mulk_i32 s0, 0x210
	v_readlane_b32 s6, v252, 19
	v_readlane_b32 s7, v252, 20
	s_nop 3
	s_add_u32 s6, s6, s0
	s_addc_u32 s7, s7, s1
	v_cmp_le_u32_e64 s[98:99], s4, v30
	v_cmp_le_u32_e64 s[100:101], s4, v31
	v_cmp_le_u32_e64 s[2:3], s4, v28
	v_writelane_b32 v39, s98, 0
	v_writelane_b32 v39, s99, 1
	v_cmp_le_u32_e64 s[98:99], s4, v29
	v_writelane_b32 v39, s100, 2
	v_writelane_b32 v39, s101, 3
	v_cmp_le_u32_e64 s[100:101], s4, v26
	v_writelane_b32 v39, s2, 4
	v_writelane_b32 v39, s3, 5
	v_cmp_le_u32_e64 s[2:3], s4, v27
	v_writelane_b32 v39, s98, 6
	v_writelane_b32 v39, s99, 7
	v_cmp_le_u32_e64 s[98:99], s4, v24
	v_writelane_b32 v39, s100, 8
	v_writelane_b32 v39, s101, 9
	v_cmp_le_u32_e64 s[100:101], s4, v25
	v_writelane_b32 v39, s2, 10
	v_writelane_b32 v39, s3, 11
	v_cmp_le_u32_e64 s[2:3], s4, v22
	v_writelane_b32 v39, s98, 12
	v_writelane_b32 v39, s99, 13
	v_cmp_le_u32_e64 s[98:99], s4, v23
	v_writelane_b32 v39, s100, 14
	v_writelane_b32 v39, s101, 15
	v_cmp_le_u32_e64 s[100:101], s4, v20
	v_writelane_b32 v39, s2, 16
	v_writelane_b32 v39, s3, 17
	v_cmp_le_u32_e64 s[2:3], s4, v21
	v_writelane_b32 v39, s98, 18
	v_writelane_b32 v39, s99, 19
	v_cmp_le_u32_e64 s[98:99], s4, v18
	v_writelane_b32 v39, s100, 20
	v_writelane_b32 v39, s101, 21
	v_cmp_le_u32_e64 s[100:101], s4, v19
	v_writelane_b32 v39, s2, 22
	v_writelane_b32 v39, s3, 23
	v_cmp_le_u32_e64 s[2:3], s4, v16
	v_writelane_b32 v39, s98, 24
	v_writelane_b32 v39, s99, 25
	v_cmp_le_u32_e64 s[98:99], s4, v17
	v_writelane_b32 v39, s100, 26
	v_writelane_b32 v39, s101, 27
	v_cmp_le_u32_e64 s[100:101], s4, v14
	v_writelane_b32 v39, s2, 28
	v_writelane_b32 v39, s3, 29
	v_cmp_le_u32_e64 s[2:3], s4, v15
	v_writelane_b32 v39, s98, 30
	v_writelane_b32 v39, s99, 31
	v_cmp_le_u32_e64 s[98:99], s4, v12
	v_writelane_b32 v39, s100, 32
	v_writelane_b32 v39, s101, 33
	v_cmp_le_u32_e64 s[100:101], s4, v13
	v_writelane_b32 v39, s2, 34
	v_writelane_b32 v39, s3, 35
	v_cmp_le_u32_e64 s[2:3], s4, v10
	v_writelane_b32 v39, s98, 36
	v_writelane_b32 v39, s99, 37
	v_cmp_le_u32_e64 s[98:99], s4, v11
	v_writelane_b32 v39, s100, 38
	v_writelane_b32 v39, s101, 39
	v_cmp_le_u32_e64 s[100:101], s4, v8
	v_writelane_b32 v39, s2, 40
	v_writelane_b32 v39, s3, 41
	v_cmp_le_u32_e64 s[2:3], s4, v9
	v_writelane_b32 v39, s98, 42
	v_writelane_b32 v39, s99, 43
	v_cmp_le_u32_e64 s[98:99], s4, v6
	v_writelane_b32 v39, s100, 44
	v_writelane_b32 v39, s101, 45
	v_cmp_le_u32_e64 s[100:101], s4, v7
	v_writelane_b32 v39, s2, 46
	v_writelane_b32 v39, s3, 47
	v_cmp_le_u32_e64 s[2:3], s4, v4
	v_writelane_b32 v39, s98, 48
	v_writelane_b32 v39, s99, 49
	v_cmp_le_u32_e64 s[98:99], s4, v5
	v_writelane_b32 v39, s100, 50
	v_writelane_b32 v39, s101, 51
	v_cmp_le_u32_e64 s[100:101], s4, v2
	v_writelane_b32 v39, s2, 52
	v_writelane_b32 v39, s3, 53
	v_cmp_le_u32_e64 s[2:3], s4, v3
	v_writelane_b32 v39, s98, 54
	v_writelane_b32 v39, s99, 55
	v_cmp_le_u32_e64 s[98:99], s4, v0
	v_writelane_b32 v39, s100, 56
	v_writelane_b32 v39, s101, 57
	v_cmp_le_u32_e64 s[100:101], s4, v1
	v_writelane_b32 v39, s2, 58
	v_writelane_b32 v39, s3, 59
	v_cmp_le_u32_e64 s[2:3], s4, v32
	v_writelane_b32 v39, s98, 60
	v_writelane_b32 v39, s99, 61
	v_writelane_b32 v39, s100, 62
	v_writelane_b32 v39, s101, 63
	v_writelane_b32 v40, s2, 0
	v_writelane_b32 v40, s3, 1
	v_lshlrev_b32_e32 v33, 2, v120
	global_store_dword v33, v39, s[6:7]
	s_mov_b64 exec, 3
	global_store_dword v33, v40, s[6:7] offset:256
	s_mov_b64 exec, -1
	v_readlane_b32 s96, v251, 36
	v_readlane_b32 s97, v251, 37
	s_movk_i32 s92, 0x1010
	s_mov_b32 s93, 0xfea1000
	s_branch .LBB0_2725

; DI void select_item(const Params& p, int isP, int sq, int c, int sub, char*) {
;     ...
;     if (exact) {
;       unsigned mn = 0xFFFFFFFFu;
; #pragma unroll
;       for (int r = 0; r < 65; ++r) mn = min(mn, v[r] >= thr ? v[r] : 0xFFFFFFFFu);
; #pragma unroll
;       for (int o = 32; o >= 1; o >>= 1) mn = min(mn, (unsigned)__shfl_xor((int)mn, o));
;       thr = __builtin_amdgcn_readfirstlane(mn);
;     }
;     int gt = 0, eq = 0;
; #pragma unroll
;     for (int r = 0; r < 65; ++r) {
;       gt += __popcll(__ballot(v[r] > thr));
;       eq += __popcll(__ballot(v[r] == thr));
;     }
;     const int need = 256 - gt;
;     int idxcut = 0x7fffffff;
;     if (eq != need) {
;       int run = 0;
;       bool done = false;
; #pragma unroll
;       for (int r = 0; r < 65; ++r) {
;         if (!done) {
;           unsigned long long m = __ballot(v[r] == thr);
;           int pc = __popcll(m);
;           if (run + pc >= need) {
;             const int k = need - run;
;             for (int t = 1; t < k; ++t) m &= m - 1ull;
;             idxcut = r * 64 + (__ffsll((long long)m) - 1);
;             done = true;
;           } else run += pc;
;         }
;       }
;     }
;     unsigned* mrowp = maskg + (long)(qrow + wid) * MW;
; #pragma unroll
;     for (int r = 0; r < 65; ++r) {
;       if (r < nr) {
;         const bool sel = (v[r] > thr) || (v[r] == thr && (r * 64 + lane) <= idxcut);
;         const unsigned long long bal = __ballot(sel);
;         if (lane == 0) *(uint2*)(mrowp + r * 2) = make_uint2((unsigned)bal, (unsigned)(bal >> 32));
;       }
;     }
.Lrx2_next:
	s_add_i32 s6, s6, -1
	s_cmp_ge_i32 s6, 0
	s_cbranch_scc1 .Lrx2_top
	s_branch .LBB0_3680
.Lrx2_fast:
	s_add_i32 s0, s72, s81
	s_mul_hi_i32 s1, s0, 0x210
	s_mulk_i32 s0, 0x210
	s_add_u32 s6, s64, s0
	s_addc_u32 s7, s65, s1
	v_cmp_le_u32_e64 s[98:99], s28, v62
	v_cmp_le_u32_e64 s[100:101], s28, v63
	v_cmp_le_u32_e64 s[2:3], s28, v60
	v_writelane_b32 v71, s98, 0
	v_writelane_b32 v71, s99, 1
	v_cmp_le_u32_e64 s[98:99], s28, v61
	v_writelane_b32 v71, s100, 2
	v_writelane_b32 v71, s101, 3
	v_cmp_le_u32_e64 s[100:101], s28, v58
	v_writelane_b32 v71, s2, 4
	v_writelane_b32 v71, s3, 5
	v_cmp_le_u32_e64 s[2:3], s28, v59
	v_writelane_b32 v71, s98, 6
	v_writelane_b32 v71, s99, 7
	v_cmp_le_u32_e64 s[98:99], s28, v56
	v_writelane_b32 v71, s100, 8
	v_writelane_b32 v71, s101, 9
	v_cmp_le_u32_e64 s[100:101], s28, v57
	v_writelane_b32 v71, s2, 10
	v_writelane_b32 v71, s3, 11
	v_cmp_le_u32_e64 s[2:3], s28, v54
	v_writelane_b32 v71, s98, 12
	v_writelane_b32 v71, s99, 13
	v_cmp_le_u32_e64 s[98:99], s28, v55
	v_writelane_b32 v71, s100, 14
	v_writelane_b32 v71, s101, 15
	v_cmp_le_u32_e64 s[100:101], s28, v52
	v_writelane_b32 v71, s2, 16
	v_writelane_b32 v71, s3, 17
	v_cmp_le_u32_e64 s[2:3], s28, v53
	v_writelane_b32 v71, s98, 18
	v_writelane_b32 v71, s99, 19
	v_cmp_le_u32_e64 s[98:99], s28, v50
	v_writelane_b32 v71, s100, 20
	v_writelane_b32 v71, s101, 21
	v_cmp_le_u32_e64 s[100:101], s28, v51
	v_writelane_b32 v71, s2, 22
	v_writelane_b32 v71, s3, 23
	v_cmp_le_u32_e64 s[2:3], s28, v48
	v_writelane_b32 v71, s98, 24
	v_writelane_b32 v71, s99, 25
	v_cmp_le_u32_e64 s[98:99], s28, v49
	v_writelane_b32 v71, s100, 26
	v_writelane_b32 v71, s101, 27
	v_cmp_le_u32_e64 s[100:101], s28, v46
	v_writelane_b32 v71, s2, 28
	v_writelane_b32 v71, s3, 29
	v_cmp_le_u32_e64 s[2:3], s28, v47
	v_writelane_b32 v71, s98, 30
	v_writelane_b32 v71, s99, 31
	v_cmp_le_u32_e64 s[98:99], s28, v44
	v_writelane_b32 v71, s100, 32
	v_writelane_b32 v71, s101, 33
	v_cmp_le_u32_e64 s[100:101], s28, v45
	v_writelane_b32 v71, s2, 34
	v_writelane_b32 v71, s3, 35
	v_cmp_le_u32_e64 s[2:3], s28, v42
	v_writelane_b32 v71, s98, 36
	v_writelane_b32 v71, s99, 37
	v_cmp_le_u32_e64 s[98:99], s28, v43
	v_writelane_b32 v71, s100, 38
	v_writelane_b32 v71, s101, 39
	v_cmp_le_u32_e64 s[100:101], s28, v40
	v_writelane_b32 v71, s2, 40
	v_writelane_b32 v71, s3, 41
	v_cmp_le_u32_e64 s[2:3], s28, v41
	v_writelane_b32 v71, s98, 42
	v_writelane_b32 v71, s99, 43
	v_cmp_le_u32_e64 s[98:99], s28, v38
	v_writelane_b32 v71, s100, 44
	v_writelane_b32 v71, s101, 45
	v_cmp_le_u32_e64 s[100:101], s28, v39
	v_writelane_b32 v71, s2, 46
	v_writelane_b32 v71, s3, 47
	v_cmp_le_u32_e64 s[2:3], s28, v34
	v_writelane_b32 v71, s98, 48
	v_writelane_b32 v71, s99, 49
	v_cmp_le_u32_e64 s[98:99], s28, v35
	v_writelane_b32 v71, s100, 50
	v_writelane_b32 v71, s101, 51
	v_cmp_le_u32_e64 s[100:101], s28, v30
	v_writelane_b32 v71, s2, 52
	v_writelane_b32 v71, s3, 53
	v_cmp_le_u32_e64 s[2:3], s28, v31
	v_writelane_b32 v71, s98, 54
	v_writelane_b32 v71, s99, 55
	v_cmp_le_u32_e64 s[98:99], s28, v28
	v_writelane_b32 v71, s100, 56
	v_writelane_b32 v71, s101, 57
	v_cmp_le_u32_e64 s[100:101], s28, v29
	v_writelane_b32 v71, s2, 58
	v_writelane_b32 v71, s3, 59
	v_cmp_le_u32_e64 s[2:3], s28, v64
	v_writelane_b32 v71, s98, 60
	v_writelane_b32 v71, s99, 61
	v_cmp_le_u32_e64 s[98:99], s28, v36
	v_writelane_b32 v71, s100, 62
	v_writelane_b32 v71, s101, 63
	v_cmp_le_u32_e64 s[100:101], s28, v37
	v_writelane_b32 v72, s2, 0
	v_writelane_b32 v72, s3, 1
	v_cmp_le_u32_e64 s[2:3], s28, v32
	v_writelane_b32 v72, s98, 2
	v_writelane_b32 v72, s99, 3
	v_cmp_le_u32_e64 s[98:99], s28, v33
	v_writelane_b32 v72, s100, 4
	v_writelane_b32 v72, s101, 5
	v_cmp_le_u32_e64 s[100:101], s28, v26
	v_writelane_b32 v72, s2, 6
	v_writelane_b32 v72, s3, 7
	v_cmp_le_u32_e64 s[2:3], s28, v27
	v_writelane_b32 v72, s98, 8
	v_writelane_b32 v72, s99, 9
	v_cmp_le_u32_e64 s[98:99], s28, v24
	v_writelane_b32 v72, s100, 10
	v_writelane_b32 v72, s101, 11
	v_cmp_le_u32_e64 s[100:101], s28, v25
	v_writelane_b32 v72, s2, 12
	v_writelane_b32 v72, s3, 13
	v_cmp_le_u32_e64 s[2:3], s28, v22
	v_writelane_b32 v72, s98, 14
	v_writelane_b32 v72, s99, 15
	v_cmp_le_u32_e64 s[98:99], s28, v23
	v_writelane_b32 v72, s100, 16
	v_writelane_b32 v72, s101, 17
	v_cmp_le_u32_e64 s[100:101], s28, v20
	v_writelane_b32 v72, s2, 18
	v_writelane_b32 v72, s3, 19
	v_cmp_le_u32_e64 s[2:3], s28, v21
	v_writelane_b32 v72, s98, 20
	v_writelane_b32 v72, s99, 21
	v_cmp_le_u32_e64 s[98:99], s28, v18
	v_writelane_b32 v72, s100, 22
	v_writelane_b32 v72, s101, 23
	v_cmp_le_u32_e64 s[100:101], s28, v19
	v_writelane_b32 v72, s2, 24
	v_writelane_b32 v72, s3, 25
	v_cmp_le_u32_e64 s[2:3], s28, v16
	v_writelane_b32 v72, s98, 26
	v_writelane_b32 v72, s99, 27
	v_cmp_le_u32_e64 s[98:99], s28, v17
	v_writelane_b32 v72, s100, 28
	v_writelane_b32 v72, s101, 29
	v_cmp_le_u32_e64 s[100:101], s28, v14
	v_writelane_b32 v72, s2, 30
	v_writelane_b32 v72, s3, 31
	v_cmp_le_u32_e64 s[2:3], s28, v15
	v_writelane_b32 v72, s98, 32
	v_writelane_b32 v72, s99, 33
	v_cmp_le_u32_e64 s[98:99], s28, v12
	v_writelane_b32 v72, s100, 34
	v_writelane_b32 v72, s101, 35
	v_cmp_le_u32_e64 s[100:101], s28, v13
	v_writelane_b32 v72, s2, 36
	v_writelane_b32 v72, s3, 37
	v_cmp_le_u32_e64 s[2:3], s28, v10
	v_writelane_b32 v72, s98, 38
	v_writelane_b32 v72, s99, 39
	v_cmp_le_u32_e64 s[98:99], s28, v11
	v_writelane_b32 v72, s100, 40
	v_writelane_b32 v72, s101, 41
	v_cmp_le_u32_e64 s[100:101], s28, v8
	v_writelane_b32 v72, s2, 42
	v_writelane_b32 v72, s3, 43
	v_cmp_le_u32_e64 s[2:3], s28, v9
	v_writelane_b32 v72, s98, 44
	v_writelane_b32 v72, s99, 45
	v_cmp_le_u32_e64 s[98:99], s28, v6
	v_writelane_b32 v72, s100, 46
	v_writelane_b32 v72, s101, 47
	v_cmp_le_u32_e64 s[100:101], s28, v7
	v_writelane_b32 v72, s2, 48
	v_writelane_b32 v72, s3, 49
	v_cmp_le_u32_e64 s[2:3], s28, v4
	v_writelane_b32 v72, s98, 50
	v_writelane_b32 v72, s99, 51
	v_cmp_le_u32_e64 s[98:99], s28, v5
	v_writelane_b32 v72, s100, 52
	v_writelane_b32 v72, s101, 53
	v_cmp_le_u32_e64 s[100:101], s28, v2
	v_writelane_b32 v72, s2, 54
	v_writelane_b32 v72, s3, 55
	v_cmp_le_u32_e64 s[2:3], s28, v3
	v_writelane_b32 v72, s98, 56
	v_writelane_b32 v72, s99, 57
	v_cmp_le_u32_e64 s[98:99], s28, v0
	v_writelane_b32 v72, s100, 58
	v_writelane_b32 v72, s101, 59
	v_cmp_le_u32_e64 s[100:101], s28, v1
	v_writelane_b32 v72, s2, 60
	v_writelane_b32 v72, s3, 61
	v_writelane_b32 v72, s98, 62
	v_writelane_b32 v72, s99, 63
	v_writelane_b32 v73, s100, 0
	v_writelane_b32 v73, s101, 1
	v_lshlrev_b32_e32 v65, 2, v117
	global_store_dword v65, v71, s[6:7]
	global_store_dword v65, v72, s[6:7] offset:256
	s_mov_b64 exec, 3
	global_store_dword v65, v73, s[6:7] offset:512
	s_mov_b64 exec, -1
	s_branch .LBB0_3527
